# LN epilogue: residual (X16) row loads issued 8 groups deep before the K-loop drain wait; hot loops kept at baseline alignment
# speedup vs baseline: 1.0007x; 1.0007x over previous
; #define PG8_WAIT_V(n) asm volatile("s_waitcnt vmcnt(" #n ")" ::: "memory")
; #define PG8_BAR __builtin_amdgcn_s_barrier()
; template <class Epi>
; __device__ __forceinline__ void gemm_phase(LAS unsigned char* lds, const Gemm g, const Order& S, const Epi& E) {
;     ...
;         if constexpr (ALIGN_EPI) { if (wr == 0) PG8_BAR; }
;         if constexpr (!Epi::AFTER_DRAIN) E(acc, cur, wr, wc, fr, fq);
;         if (!has_next) break;
;         if (!(Epi::KEEP_ACC && nxt.z != 0)) {
; #pragma unroll
;         for (int a = 0; a < 2; ++a)
; #pragma unroll
;             for (int b = 0; b < 2; ++b)
; #pragma unroll
;                 for (int m = 0; m < 4; ++m)
; #pragma unroll
;                     for (int n = 0; n < 2; ++n) acc[a][b][m][n] = (f32x4){0.f, 0.f, 0.f, 0.f};
;         }
;         cur = nxt; cA = nA; cB = nB; ++ui;
;         if constexpr (ALIGN_EPI) { if (wr == 1) PG8_BAR; }
;     }
;     PG8_WAIT_V(0);
;     if constexpr (!ALIGN_EPI) { if (wr == 0) PG8_BAR; }
;     PG8_BAR;
;     if constexpr (Epi::AFTER_DRAIN) E.fused(acc, cur, wr, wc, fr, fq, lds, wid, lane);
.LBB0_262:
	s_andn2_b64 vcc, exec, s[4:5]
	s_cbranch_vccz .LBB0_387
	s_branch .LBB0_421
	s_nop 0
	s_nop 0
	s_nop 0
	s_nop 0
	s_nop 0
	s_nop 0
	s_nop 0
	s_nop 0
	s_nop 0
	s_nop 0
	s_nop 0
	s_nop 0
	s_nop 0
	s_nop 0
	s_nop 0
	s_nop 0
	s_nop 0
	s_nop 0
	s_nop 0
	s_nop 0
	s_nop 0
	s_nop 0
	s_nop 0
	s_nop 0
	s_nop 0
	s_nop 0
	s_nop 0
	s_nop 0
	s_nop 0
	s_nop 0
	s_nop 0
	s_nop 0
	s_nop 0
	s_nop 0
	s_nop 0
	s_nop 0
	s_nop 0
	s_nop 0
	s_nop 0
	s_nop 0
	s_nop 0
	s_nop 0
	s_nop 0
	s_nop 0
	s_nop 0
	s_nop 0
	s_nop 0
